# DFT loop: sign flips folded into v_cvt_pk neg modifiers (11 xors removed)
# speedup vs baseline: 1.0293x; 1.0004x over previous
; #define MFMA32(a, b, c) __builtin_amdgcn_mfma_f32_32x32x16_bf16((a), (b), (c), 0, 0, 0)
; DI unsigned pk2(float a, float b) { f32v2 v = {a, b}; return __builtin_bit_cast(unsigned, __builtin_convertvector(v, bf16v2)); }
;   DI void gen(int kt, int q, float cd, float sd, uint4& rc, uint4& rs) const {
;     const int row = q >> 2, seg = q & 3;
;     const int ks = ks0 + row; const int sst = kt * 32 + seg * 8;
;     const int idx = (ks * sst) & (S - 1);
;     const float f = (float)idx * invS;
;     const float c0 = __builtin_amdgcn_cosf(f), s0 = __builtin_amdgcn_sinf(f);
;     const float c1 = c0 * cd - s0 * sd, s1 = s0 * cd + c0 * sd;
;     const float c2 = c1 * cd - s1 * sd, s2 = s1 * cd + c1 * sd;
;     const float c3 = c2 * cd - s2 * sd, s3 = s2 * cd + c2 * sd;
;     const float c4 = c3 * cd - s3 * sd, s4 = s3 * cd + c3 * sd;
;     const float c5 = c4 * cd - s4 * sd, s5 = s4 * cd + c4 * sd;
;     const float c6 = c5 * cd - s5 * sd, s6 = s5 * cd + c5 * sd;
;     const float c7 = c6 * cd - s6 * sd, s7 = s6 * cd + c6 * sd;
;     rc = make_uint4(pk2(c0, c1), pk2(c2, c3), pk2(c4, c5), pk2(c6, c7));
;     rs = make_uint4(pk2(-s0, -s1), pk2(-s2, -s3), pk2(-s4, -s5), pk2(-s6, -s7));
;   }
;   DI void load(int kt, int tid, uint4& r0, uint4& r1, uint4& r2, uint4& r3) const { gen(kt, tid, cd0, sd0, r0, r1); gen(kt, tid + 256, cd1, sd1, r2, r3); }
; DI void dft_mma(const bf16_t* sA, f32x16 (&accP)[2][2], f32x16 (&accQ)[2][2], int moff, int noff) {
;   const bf16_t* sB = sA + TILE_E;
; #pragma unroll
;   for (int kk = 0; kk < 4; kk++) {
;     bf16x8 fm0 = *(const bf16x8*)(sB + moff + kk * 16);
;     bf16x8 fm1 = *(const bf16x8*)(sB + moff + 32 * LDT + kk * 16);
;     bf16x8 fn0 = *(const bf16x8*)(sA + noff + kk * 16);
;     bf16x8 fn1 = *(const bf16x8*)(sA + noff + 32 * LDT + kk * 16);
;     if (kk < 2) {
;       accP[0][0] = MFMA32(fm0, fn0, accP[0][0]); accP[0][1] = MFMA32(fm0, fn1, accP[0][1]);
;       accP[1][0] = MFMA32(fm1, fn0, accP[1][0]); accP[1][1] = MFMA32(fm1, fn1, accP[1][1]);
;     } else {
;       accQ[0][0] = MFMA32(fm0, fn0, accQ[0][0]); accQ[0][1] = MFMA32(fm0, fn1, accQ[0][1]);
;       accQ[1][0] = MFMA32(fm1, fn0, accQ[1][0]); accQ[1][1] = MFMA32(fm1, fn1, accQ[1][1]);
;     }
;   }
; }
.LBB0_54:
	ds_read_b128 v[146:149], v215 offset:18432
	ds_read_b128 v[150:153], v217
	ds_read_b128 v[154:157], v217 offset:4608
	v_and_b32_e32 v158, s29, v223
	v_and_b32_e32 v159, s29, v219
	s_add_i32 s11, s10, -1
	s_waitcnt lgkmcnt(1)
	v_mfma_f32_32x32x16_bf16 v[114:129], v[146:149], v[150:153], v[114:129]
	s_min_u32 s90, s11, s93
	s_lshl_b64 s[8:9], s[90:91], 10
	v_add_u32_e32 v219, v219, v221
	v_add_u32_e32 v223, v223, v239
	s_waitcnt lgkmcnt(0)
	v_mfma_f32_32x32x16_bf16 v[50:65], v[146:149], v[154:157], v[50:65]
	ds_read_b128 v[146:149], v215 offset:23040
	s_waitcnt lgkmcnt(0)
	v_mfma_f32_32x32x16_bf16 v[82:97], v[146:149], v[150:153], v[82:97]
	v_mfma_f32_32x32x16_bf16 v[18:33], v[146:149], v[154:157], v[18:33]
	ds_read_b128 v[146:149], v215 offset:18496
	ds_read_b128 v[150:153], v217 offset:64
	ds_read_b128 v[154:157], v217 offset:4672
	s_waitcnt lgkmcnt(1)
	v_mfma_f32_32x32x16_bf16 v[98:113], v[146:149], v[150:153], v[98:113]
	s_waitcnt lgkmcnt(0)
	v_mfma_f32_32x32x16_bf16 v[34:49], v[146:149], v[154:157], v[34:49]
	ds_read_b128 v[146:149], v215 offset:23104
	s_waitcnt lgkmcnt(0)
	v_mfma_f32_32x32x16_bf16 v[66:81], v[146:149], v[150:153], v[66:81]
	v_mfma_f32_32x32x16_bf16 v[2:17], v[146:149], v[154:157], v[2:17]
	ds_read_b128 v[146:149], v215 offset:18464
	ds_read_b128 v[150:153], v217 offset:32
	ds_read_b128 v[154:157], v217 offset:4640
	ds_read_b128 v[162:165], v215 offset:23072
	ds_read_b128 v[166:169], v215 offset:18528
	ds_read_b128 v[170:173], v217 offset:96
	ds_read_b128 v[176:179], v217 offset:4704
	ds_read_b128 v[226:229], v215 offset:23136
	s_waitcnt lgkmcnt(6)
	v_mfma_f32_32x32x16_bf16 v[114:129], v[146:149], v[150:153], v[114:129]
	s_waitcnt lgkmcnt(5)
	v_mfma_f32_32x32x16_bf16 v[50:65], v[146:149], v[154:157], v[50:65]
	v_cvt_f32_u32_e32 v146, v158
	v_cvt_f32_u32_e32 v147, v159
	v_mul_f32_e32 v146, v250, v146
	v_mul_f32_e32 v147, v250, v147
	v_sin_f32_e32 v161, v146
	v_cos_f32_e32 v160, v146
	v_cos_f32_e32 v146, v147
	v_sin_f32_e32 v147, v147
	s_waitcnt lgkmcnt(4)
	v_mfma_f32_32x32x16_bf16 v[82:97], v[162:165], v[150:153], v[82:97]
	v_mul_f32_e32 v148, v187, v161
	v_mov_b32_e32 v150, v161
	v_mov_b32_e32 v151, v160
	v_mul_f32_e32 v152, v187, v160
	v_mov_b32_e32 v158, v147
	v_mov_b32_e32 v159, v146
	v_pk_fma_f32 v[180:181], v[186:187], v[160:161], v[148:149] op_sel_hi:[1,1,0] neg_lo:[0,0,1] neg_hi:[0,0,1]
	v_mfma_f32_32x32x16_bf16 v[18:33], v[162:165], v[154:157], v[18:33]
	v_mul_f32_e32 v156, v189, v147
	v_mul_f32_e32 v164, v189, v146
	v_fma_f32 v154, v186, v150, v152
	v_fma_f32 v155, v187, v151, v152
	v_fma_f32 v162, v188, v146, -v156
	v_fma_f32 v163, v189, v147, -v156
	v_pk_fma_f32 v[174:175], v[188:189], v[158:159], v[164:165] op_sel_hi:[1,1,0]
	v_mov_b32_e32 v181, v154
	v_mov_b32_e32 v155, v180
	v_mov_b32_e32 v163, v174
	v_pk_mul_f32 v[148:149], v[194:195], v[180:181]
	v_mov_b32_e32 v175, v162
	v_pk_mul_f32 v[150:151], v[200:201], v[162:163]
	v_pk_fma_f32 v[152:153], v[192:193], v[154:155], v[148:149]
	v_pk_fma_f32 v[156:157], v[192:193], v[154:155], v[148:149] neg_lo:[0,0,1] neg_hi:[0,0,1]
	v_pk_fma_f32 v[148:149], v[198:199], v[174:175], v[150:151]
	v_pk_fma_f32 v[164:165], v[198:199], v[174:175], v[150:151] neg_lo:[0,0,1] neg_hi:[0,0,1]
	v_mov_b32_e32 v150, v152
	v_pk_mov_b32 v[152:153], v[156:157], v[152:153] op_sel:[1,0]
	s_waitcnt lgkmcnt(2)
	v_mfma_f32_32x32x16_bf16 v[98:113], v[166:169], v[170:173], v[98:113]
	v_mov_b32_e32 v151, v157
	v_mul_f32_e64 v152, v194, v152
	v_mul_f32_e64 v153, v195, v153
	v_cvt_pk_bf16_f32 v162, v146, v162
	v_xor_b32_e32 v175, 0x80000000, v147
	s_waitcnt lgkmcnt(0)
; #define MFMA32(a, b, c) __builtin_amdgcn_mfma_f32_32x32x16_bf16((a), (b), (c), 0, 0, 0)
; DI unsigned pk2(float a, float b) { f32v2 v = {a, b}; return __builtin_bit_cast(unsigned, __builtin_convertvector(v, bf16v2)); }
;   DI void gen(int kt, int q, float cd, float sd, uint4& rc, uint4& rs) const {
;     const int row = q >> 2, seg = q & 3;
;     const int ks = ks0 + row; const int sst = kt * 32 + seg * 8;
;     const int idx = (ks * sst) & (S - 1);
;     const float f = (float)idx * invS;
;     const float c0 = __builtin_amdgcn_cosf(f), s0 = __builtin_amdgcn_sinf(f);
;     const float c1 = c0 * cd - s0 * sd, s1 = s0 * cd + c0 * sd;
;     const float c2 = c1 * cd - s1 * sd, s2 = s1 * cd + c1 * sd;
;     const float c3 = c2 * cd - s2 * sd, s3 = s2 * cd + c2 * sd;
;     const float c4 = c3 * cd - s3 * sd, s4 = s3 * cd + c3 * sd;
;     const float c5 = c4 * cd - s4 * sd, s5 = s4 * cd + c4 * sd;
;     const float c6 = c5 * cd - s5 * sd, s6 = s5 * cd + c5 * sd;
;     const float c7 = c6 * cd - s6 * sd, s7 = s6 * cd + c6 * sd;
;     rc = make_uint4(pk2(c0, c1), pk2(c2, c3), pk2(c4, c5), pk2(c6, c7));
;     rs = make_uint4(pk2(-s0, -s1), pk2(-s2, -s3), pk2(-s4, -s5), pk2(-s6, -s7));
;   }
;   DI void load(int kt, int tid, uint4& r0, uint4& r1, uint4& r2, uint4& r3) const { gen(kt, tid, cd0, sd0, r0, r1); gen(kt, tid + 256, cd1, sd1, r2, r3); }
; DI void dft_mma(const bf16_t* sA, f32x16 (&accP)[2][2], f32x16 (&accQ)[2][2], int moff, int noff) {
;   const bf16_t* sB = sA + TILE_E;
; #pragma unroll
;   for (int kk = 0; kk < 4; kk++) {
;     bf16x8 fm0 = *(const bf16x8*)(sB + moff + kk * 16);
;     bf16x8 fm1 = *(const bf16x8*)(sB + moff + 32 * LDT + kk * 16);
;     bf16x8 fn0 = *(const bf16x8*)(sA + noff + kk * 16);
;     bf16x8 fn1 = *(const bf16x8*)(sA + noff + 32 * LDT + kk * 16);
;     if (kk < 2) {
;       accP[0][0] = MFMA32(fm0, fn0, accP[0][0]); accP[0][1] = MFMA32(fm0, fn1, accP[0][1]);
;       accP[1][0] = MFMA32(fm1, fn0, accP[1][0]); accP[1][1] = MFMA32(fm1, fn1, accP[1][1]);
;     } else {
;       accQ[0][0] = MFMA32(fm0, fn0, accQ[0][0]); accQ[0][1] = MFMA32(fm0, fn1, accQ[0][1]);
;       accQ[1][0] = MFMA32(fm1, fn0, accQ[1][0]); accQ[1][1] = MFMA32(fm1, fn1, accQ[1][1]);
;     }
;   }
	v_mfma_f32_32x32x16_bf16 v[66:81], v[226:229], v[170:173], v[66:81]
	v_mov_b32_e32 v170, v148
	v_pk_mov_b32 v[148:149], v[164:165], v[148:149] op_sel:[1,0]
	v_mov_b32_e32 v171, v165
	v_mfma_f32_32x32x16_bf16 v[34:49], v[166:169], v[176:179], v[34:49]
	v_mul_f32_e64 v166, v200, v148
	v_mul_f32_e64 v167, v201, v149
	v_fma_f32 v148, v192, v150, v152
	v_fma_f32 v149, v193, v151, v153
	v_fma_f32 v152, v192, v150, -v152
	v_fma_f32 v153, v193, v151, -v153
	v_mov_b32_e32 v158, v148
	v_pk_mov_b32 v[168:169], v[152:153], v[148:149] op_sel:[1,0]
	v_mov_b32_e32 v159, v153
	v_lshl_or_b32 v149, s90, 5, v249
	v_mfma_f32_32x32x16_bf16 v[2:17], v[226:229], v[176:179], v[2:17]
	v_cvt_pk_bf16_f32 v227, v157, v153
	v_mul_f32_e64 v152, v194, v168
	v_mul_f32_e64 v153, v195, v169
	v_fma_f32 v178, v198, v170, v166
	v_fma_f32 v179, v199, v171, v167
	v_pk_fma_f32 v[156:157], v[192:193], v[158:159], v[152:153]
	v_pk_fma_f32 v[168:169], v[192:193], v[158:159], v[152:153] neg_lo:[0,0,1] neg_hi:[0,0,1]
	v_mov_b32_e32 v152, v156
	v_pk_mov_b32 v[156:157], v[168:169], v[156:157] op_sel:[1,0]
	v_mov_b32_e32 v153, v169
	v_pk_mul_f32 v[156:157], v[194:195], v[156:157]
	v_pk_fma_f32 v[166:167], v[198:199], v[170:171], v[166:167] neg_lo:[0,0,1] neg_hi:[0,0,1]
	v_pk_fma_f32 v[158:159], v[192:193], v[152:153], v[156:157]
	v_pk_fma_f32 v[156:157], v[192:193], v[152:153], v[156:157] neg_lo:[0,0,1] neg_hi:[0,0,1]
	v_mov_b32_e32 v168, v158
	v_cvt_pk_bf16_f32 v228, v169, v157
	v_mov_b32_e32 v169, v157
	v_pk_mov_b32 v[156:157], v[156:157], v[158:159] op_sel:[1,0]
	v_cvt_pk_bf16_f32 v163, v165, v167
	v_pk_mul_f32 v[172:173], v[194:195], v[156:157]
	v_cvt_pk_bf16_f32 v226, v160, v180
	v_pk_fma_f32 v[156:157], v[192:193], v[168:169], v[172:173]
	v_pk_fma_f32 v[168:169], v[192:193], v[168:169], v[172:173] neg_lo:[0,0,1] neg_hi:[0,0,1]
	v_mul_f32_e32 v164, v196, v156
	v_mov_b32_e32 v157, v169
	v_pk_fma_f32 v[172:173], v[196:197], v[156:157], v[164:165] op_sel_hi:[1,1,0] neg_lo:[0,0,1] neg_hi:[0,0,1]
	v_mov_b32_e32 v168, v178
	v_cvt_pk_bf16_f32 v229, v169, v173
	v_pk_mov_b32 v[172:173], v[166:167], v[178:179] op_sel:[1,0]
	v_mov_b32_e32 v169, v167
	v_pk_mul_f32 v[172:173], v[200:201], v[172:173]
	ds_write_b128 v212, v[226:229] offset:36864
	v_pk_fma_f32 v[176:177], v[198:199], v[168:169], v[172:173]
	v_pk_fma_f32 v[172:173], v[198:199], v[168:169], v[172:173] neg_lo:[0,0,1] neg_hi:[0,0,1]
	v_mov_b32_e32 v168, v176
	v_pk_mov_b32 v[164:165], v[172:173], v[176:177] op_sel:[1,0]
	v_mov_b32_e32 v169, v173
	v_pk_mul_f32 v[166:167], v[200:201], v[164:165]
	s_waitcnt vmcnt(3)
	ds_write_b128 v214, v[142:145] offset:55296
	v_pk_fma_f32 v[176:177], v[198:199], v[168:169], v[166:167] neg_lo:[0,0,1] neg_hi:[0,0,1]
	v_xor_b32_e32 v159, 0x80000000, v161
	v_cvt_pk_bf16_f32 v164, v173, v177
	v_pk_fma_f32 v[172:173], v[198:199], v[168:169], v[166:167]
	v_mov_b32_e32 v231, v177
	v_pk_mov_b32 v[166:167], v[176:177], v[172:173] op_sel:[1,0]
	v_mov_b32_e32 v230, v172
	v_pk_mul_f32 v[176:177], v[200:201], v[166:167]
	v_mul_lo_u32 v155, v149, v251
	v_pk_fma_f32 v[166:167], v[198:199], v[230:231], v[176:177]
	v_pk_fma_f32 v[176:177], v[198:199], v[230:231], v[176:177] neg_lo:[0,0,1] neg_hi:[0,0,1]
	v_mul_lo_u32 v149, v149, v252
	v_mov_b32_e32 v167, v177
	v_mul_f32_e32 v176, v210, v166
	v_pk_fma_f32 v[230:231], v[210:211], v[166:167], v[176:177] op_sel_hi:[1,1,0] neg_lo:[0,0,1] neg_hi:[0,0,1]
	v_or_b32_e32 v176, s8, v0
	v_cvt_pk_bf16_f32 v165, v177, v231
	v_mov_b32_e32 v177, s9
	v_lshl_add_u64 v[142:143], v[176:177], 0, v[202:203]
	v_lshl_add_u64 v[144:145], v[176:177], 0, v[204:205]
	v_lshl_add_u64 v[160:161], v[176:177], 0, v[206:207]
	v_lshl_add_u64 v[176:177], v[176:177], 0, v[208:209]
	v_lshlrev_b64 v[142:143], 6, v[142:143]
	v_lshlrev_b64 v[176:177], 6, v[176:177]
	v_and_b32_e32 v146, s29, v155
	v_and_b32_e32 v149, s29, v149
	v_lshlrev_b64 v[144:145], 6, v[144:145]
	v_lshl_add_u64 v[226:227], v[224:225], 0, v[142:143]
	v_lshl_add_u64 v[142:143], v[224:225], 0, v[176:177]
	v_cvt_f32_u32_e32 v155, v146
	v_cvt_f32_u32_e32 v173, v149
	v_lshl_add_u64 v[228:229], v[224:225], 0, v[144:145]
	v_xor_b32_e32 v144, 0x80000000, v148
	global_load_dwordx4 v[146:149], v[142:143], off
	v_pk_add_f32 v[142:143], v[150:151], 0 neg_lo:[1,1] neg_hi:[1,1]

; DI unsigned pk2(float a, float b) { f32v2 v = {a, b}; return __builtin_bit_cast(unsigned, __builtin_convertvector(v, bf16v2)); }
;   DI void load(int kt, int tid, uint4& r0, uint4& r1, uint4& r2, uint4& r3) const { r0 = ld1(kt, 0, tid); r1 = ld1(kt, 1, tid); r2 = ld1(kt, 2, tid); r3 = ld1(kt, 3, tid); }
;   DI void load(int kt, int tid, uint4& r0, uint4& r1, uint4& r2, uint4& r3) const { r0 = ld1(kt, 0, tid); r1 = ld1(kt, 1, tid); r2 = ld1(kt, 2, tid); r3 = ld1(kt, 3, tid); }
;   DI void load(int kt, int tid, uint4& r0, uint4& r1, uint4& r2, uint4& r3) const { r0 = ld1(kt, 0, tid); r1 = ld1(kt, 1, tid); r2 = ld1(kt, 2, tid); r3 = ld1(kt, 3, tid); }
;   DI void load(int kt, int tid, uint4& r0, uint4& r1, uint4& r2, uint4& r3) const { r0 = ld1(kt, 0, tid); r1 = ld1(kt, 1, tid); r2 = ld1(kt, 2, tid); r3 = ld1(kt, 3, tid); }
;   DI void gen(int kt, int q, float cd, float sd, uint4& rc, uint4& rs) const {
;     const int row = q >> 2, seg = q & 3;
;     const int ks = ks0 + row; const int sst = kt * 32 + seg * 8;
;     const int idx = (ks * sst) & (S - 1);
;     const float f = (float)idx * invS;
;     const float c0 = __builtin_amdgcn_cosf(f), s0 = __builtin_amdgcn_sinf(f);
;     const float c1 = c0 * cd - s0 * sd, s1 = s0 * cd + c0 * sd;
;     const float c2 = c1 * cd - s1 * sd, s2 = s1 * cd + c1 * sd;
;     const float c3 = c2 * cd - s2 * sd, s3 = s2 * cd + c2 * sd;
;     const float c4 = c3 * cd - s3 * sd, s4 = s3 * cd + c3 * sd;
;     const float c5 = c4 * cd - s4 * sd, s5 = s4 * cd + c4 * sd;
;     const float c6 = c5 * cd - s5 * sd, s6 = s5 * cd + c5 * sd;
;     const float c7 = c6 * cd - s6 * sd, s7 = s6 * cd + c6 * sd;
;     rc = make_uint4(pk2(c0, c1), pk2(c2, c3), pk2(c4, c5), pk2(c6, c7));
;     rs = make_uint4(pk2(-s0, -s1), pk2(-s2, -s3), pk2(-s4, -s5), pk2(-s6, -s7));
;   }
;   DI void load(int kt, int tid, uint4& r0, uint4& r1, uint4& r2, uint4& r3) const { gen(kt, tid, cd0, sd0, r0, r1); gen(kt, tid + 256, cd1, sd1, r2, r3); }
	v_cvt_pk_bf16_f32 v143, v142, v144
	v_pk_add_f32 v[144:145], v[152:153], 0 neg_lo:[1,1] neg_hi:[1,1]
	v_lshlrev_b64 v[160:161], 6, v[160:161]
	v_cvt_pk_bf16_f32 v144, v144, -v158
	v_pk_mul_f32 v[150:151], v[186:187], v[156:157]
	v_pk_add_f32 v[156:157], v[156:157], 0 neg_lo:[1,1] neg_hi:[1,1]
	v_add_f32_e32 v142, v150, v151
	v_xor_b32_e32 v142, 0x80000000, v142
	v_cvt_pk_bf16_f32 v145, v156, v142

; DI unsigned pk2(float a, float b) { f32v2 v = {a, b}; return __builtin_bit_cast(unsigned, __builtin_convertvector(v, bf16v2)); }
;   DI void load(int kt, int tid, uint4& r0, uint4& r1, uint4& r2, uint4& r3) const { r0 = ld1(kt, 0, tid); r1 = ld1(kt, 1, tid); r2 = ld1(kt, 2, tid); r3 = ld1(kt, 3, tid); }
;   DI void load(int kt, int tid, uint4& r0, uint4& r1, uint4& r2, uint4& r3) const { r0 = ld1(kt, 0, tid); r1 = ld1(kt, 1, tid); r2 = ld1(kt, 2, tid); r3 = ld1(kt, 3, tid); }
;   DI void load(int kt, int tid, uint4& r0, uint4& r1, uint4& r2, uint4& r3) const { r0 = ld1(kt, 0, tid); r1 = ld1(kt, 1, tid); r2 = ld1(kt, 2, tid); r3 = ld1(kt, 3, tid); }
;   DI void load(int kt, int tid, uint4& r0, uint4& r1, uint4& r2, uint4& r3) const { r0 = ld1(kt, 0, tid); r1 = ld1(kt, 1, tid); r2 = ld1(kt, 2, tid); r3 = ld1(kt, 3, tid); }
; #define GEMM_ST1(sA_, i_, va_, vb_) { int row, kc; la.pos(i_, tid, row, kc); *(uint4*)((sA_) + row * LDT + kc * 8) = va_; \
;     lb.pos(i_, tid, row, kc); *(uint4*)((sA_) + TILE_E + row * LDT + kc * 8) = vb_; }
;   DI void gen(int kt, int q, float cd, float sd, uint4& rc, uint4& rs) const {
;     const int row = q >> 2, seg = q & 3;
;     const int ks = ks0 + row; const int sst = kt * 32 + seg * 8;
;     const int idx = (ks * sst) & (S - 1);
;     const float f = (float)idx * invS;
;     const float c0 = __builtin_amdgcn_cosf(f), s0 = __builtin_amdgcn_sinf(f);
;     const float c1 = c0 * cd - s0 * sd, s1 = s0 * cd + c0 * sd;
;     const float c2 = c1 * cd - s1 * sd, s2 = s1 * cd + c1 * sd;
;     const float c3 = c2 * cd - s2 * sd, s3 = s2 * cd + c2 * sd;
;     const float c4 = c3 * cd - s3 * sd, s4 = s3 * cd + c3 * sd;
;     const float c5 = c4 * cd - s4 * sd, s5 = s4 * cd + c4 * sd;
;     const float c6 = c5 * cd - s5 * sd, s6 = s5 * cd + c5 * sd;
;     const float c7 = c6 * cd - s6 * sd, s7 = s6 * cd + c6 * sd;
;     rc = make_uint4(pk2(c0, c1), pk2(c2, c3), pk2(c4, c5), pk2(c6, c7));
;     rs = make_uint4(pk2(-s0, -s1), pk2(-s2, -s3), pk2(-s4, -s5), pk2(-s6, -s7));
;   }
;   DI void load(int kt, int tid, uint4& r0, uint4& r1, uint4& r2, uint4& r3) const { gen(kt, tid, cd0, sd0, r0, r1); gen(kt, tid + 256, cd1, sd1, r2, r3); }
; DI void dft_item(const Params& P, int g, int b, int ml, int ntc, bf16_t* smem) {
;     ...
;       GEMM_ST1(buf1, 0, a00, b10) GEMM_ST1(buf1, 1, a01, b11) GEMM_ST1(buf1, 2, a02, b12) GEMM_ST1(buf1, 3, a03, b13)
	v_cvt_pk_bf16_f32 v142, v159, -v154
	ds_write_b128 v212, v[142:145] offset:36928

; DI unsigned pk2(float a, float b) { f32v2 v = {a, b}; return __builtin_bit_cast(unsigned, __builtin_convertvector(v, bf16v2)); }
;   DI void load(int kt, int tid, uint4& r0, uint4& r1, uint4& r2, uint4& r3) const { r0 = ld1(kt, 0, tid); r1 = ld1(kt, 1, tid); r2 = ld1(kt, 2, tid); r3 = ld1(kt, 3, tid); }
;   DI void load(int kt, int tid, uint4& r0, uint4& r1, uint4& r2, uint4& r3) const { r0 = ld1(kt, 0, tid); r1 = ld1(kt, 1, tid); r2 = ld1(kt, 2, tid); r3 = ld1(kt, 3, tid); }
;   DI void load(int kt, int tid, uint4& r0, uint4& r1, uint4& r2, uint4& r3) const { r0 = ld1(kt, 0, tid); r1 = ld1(kt, 1, tid); r2 = ld1(kt, 2, tid); r3 = ld1(kt, 3, tid); }
;   DI void load(int kt, int tid, uint4& r0, uint4& r1, uint4& r2, uint4& r3) const { r0 = ld1(kt, 0, tid); r1 = ld1(kt, 1, tid); r2 = ld1(kt, 2, tid); r3 = ld1(kt, 3, tid); }
;   DI void gen(int kt, int q, float cd, float sd, uint4& rc, uint4& rs) const {
;     const int row = q >> 2, seg = q & 3;
;     const int ks = ks0 + row; const int sst = kt * 32 + seg * 8;
;     const int idx = (ks * sst) & (S - 1);
;     const float f = (float)idx * invS;
;     const float c0 = __builtin_amdgcn_cosf(f), s0 = __builtin_amdgcn_sinf(f);
;     const float c1 = c0 * cd - s0 * sd, s1 = s0 * cd + c0 * sd;
;     const float c2 = c1 * cd - s1 * sd, s2 = s1 * cd + c1 * sd;
;     const float c3 = c2 * cd - s2 * sd, s3 = s2 * cd + c2 * sd;
;     const float c4 = c3 * cd - s3 * sd, s4 = s3 * cd + c3 * sd;
;     const float c5 = c4 * cd - s4 * sd, s5 = s4 * cd + c4 * sd;
;     const float c6 = c5 * cd - s5 * sd, s6 = s5 * cd + c5 * sd;
;     const float c7 = c6 * cd - s6 * sd, s7 = s6 * cd + c6 * sd;
;     rc = make_uint4(pk2(c0, c1), pk2(c2, c3), pk2(c4, c5), pk2(c6, c7));
;     rs = make_uint4(pk2(-s0, -s1), pk2(-s2, -s3), pk2(-s4, -s5), pk2(-s6, -s7));
;   }
;   DI void load(int kt, int tid, uint4& r0, uint4& r1, uint4& r2, uint4& r3) const { gen(kt, tid, cd0, sd0, r0, r1); gen(kt, tid + 256, cd1, sd1, r2, r3); }
	v_pk_add_f32 v[144:145], v[170:171], 0 neg_lo:[1,1] neg_hi:[1,1]
	v_lshl_add_u64 v[160:161], v[224:225], 0, v[160:161]
	v_cvt_pk_bf16_f32 v143, v144, -v178
	v_pk_add_f32 v[144:145], v[168:169], 0 neg_lo:[1,1] neg_hi:[1,1]
	v_pk_mul_f32 v[168:169], v[188:189], v[166:167]
	v_mul_f32_e32 v155, v250, v155
	v_add_f32_e32 v145, v168, v169
	v_mul_f32_e32 v158, v250, v173
	v_xor_b32_e32 v173, 0x80000000, v174

; DI unsigned pk2(float a, float b) { f32v2 v = {a, b}; return __builtin_bit_cast(unsigned, __builtin_convertvector(v, bf16v2)); }
;   DI void load(int kt, int tid, uint4& r0, uint4& r1, uint4& r2, uint4& r3) const { r0 = ld1(kt, 0, tid); r1 = ld1(kt, 1, tid); r2 = ld1(kt, 2, tid); r3 = ld1(kt, 3, tid); }
;   DI void gen(int kt, int q, float cd, float sd, uint4& rc, uint4& rs) const {
;     const int row = q >> 2, seg = q & 3;
;     const int ks = ks0 + row; const int sst = kt * 32 + seg * 8;
;     const int idx = (ks * sst) & (S - 1);
;     const float f = (float)idx * invS;
;     const float c0 = __builtin_amdgcn_cosf(f), s0 = __builtin_amdgcn_sinf(f);
;     const float c1 = c0 * cd - s0 * sd, s1 = s0 * cd + c0 * sd;
;     const float c2 = c1 * cd - s1 * sd, s2 = s1 * cd + c1 * sd;
;     const float c3 = c2 * cd - s2 * sd, s3 = s2 * cd + c2 * sd;
;     const float c4 = c3 * cd - s3 * sd, s4 = s3 * cd + c3 * sd;
;     const float c5 = c4 * cd - s4 * sd, s5 = s4 * cd + c4 * sd;
;     const float c6 = c5 * cd - s5 * sd, s6 = s5 * cd + c5 * sd;
;     const float c7 = c6 * cd - s6 * sd, s7 = s6 * cd + c6 * sd;
;     rc = make_uint4(pk2(c0, c1), pk2(c2, c3), pk2(c4, c5), pk2(c6, c7));
;     rs = make_uint4(pk2(-s0, -s1), pk2(-s2, -s3), pk2(-s4, -s5), pk2(-s6, -s7));
;   }
;   DI void load(int kt, int tid, uint4& r0, uint4& r1, uint4& r2, uint4& r3) const { gen(kt, tid, cd0, sd0, r0, r1); gen(kt, tid + 256, cd1, sd1, r2, r3); }
; DI void dft_item(const Params& P, int g, int b, int ml, int ntc, bf16_t* smem) {
;     ...
;     for (int kt = 0; kt < nk; kt += 2) {
;       { const int k2 = (kt + 2 < nk) ? kt + 2 : last; lb.load(k2, tid, b00, b01, b02, b03); }
;       dft_mma(buf0, accP, accQ, moff, noff);
;       la.load(kt + 1, tid, a00, a01, a02, a03);
;       GEMM_ST1(buf1, 0, a00, b10) GEMM_ST1(buf1, 1, a01, b11) GEMM_ST1(buf1, 2, a02, b12) GEMM_ST1(buf1, 3, a03, b13)
;       __syncthreads();
;       { const int k3 = (kt + 3 < nk) ? kt + 3 : last; lb.load(k3, tid, b10, b11, b12, b13); }
;       dft_mma(buf1, accP, accQ, moff, noff);
;       { const int k2 = (kt + 2 < nk) ? kt + 2 : last; la.load(k2, tid, a00, a01, a02, a03); }
;       GEMM_ST1(buf0, 0, a00, b00) GEMM_ST1(buf0, 1, a01, b01) GEMM_ST1(buf0, 2, a02, b02) GEMM_ST1(buf0, 3, a03, b03)
;       __syncthreads();
	v_pk_add_f32 v[166:167], v[166:167], 0 neg_lo:[1,1] neg_hi:[1,1]
	v_xor_b32_e32 v145, 0x80000000, v145
	global_load_dwordx4 v[150:153], v[160:161], off
	v_cos_f32_e32 v180, v155
	v_sin_f32_e32 v181, v155
	v_cos_f32_e32 v176, v158
	v_sin_f32_e32 v177, v158
	global_load_dwordx4 v[154:157], v[228:229], off
	global_load_dwordx4 v[158:161], v[226:227], off
	v_cvt_pk_bf16_f32 v142, v175, v173
	v_cvt_pk_bf16_f32 v144, v144, -v172
	v_cvt_pk_bf16_f32 v145, v166, v145
	s_waitcnt vmcnt(6)
	ds_write_b128 v216, v[130:133] offset:55296
	ds_write_b128 v218, v[162:165] offset:36864
	s_waitcnt vmcnt(5)
	ds_write_b128 v220, v[134:137] offset:55296
	ds_write_b128 v218, v[142:145] offset:36928
	s_waitcnt vmcnt(4)
	ds_write_b128 v222, v[138:141] offset:55296
	s_waitcnt lgkmcnt(0)
	s_barrier
	ds_read_b128 v[130:133], v215 offset:55296
	ds_read_b128 v[134:137], v217 offset:36864
	ds_read_b128 v[138:141], v217 offset:41472
	s_waitcnt lgkmcnt(1)
	v_mfma_f32_32x32x16_bf16 v[114:129], v[130:133], v[134:137], v[114:129]
	v_mov_b32_e32 v168, v177
	v_mov_b32_e32 v169, v176
	v_mul_f32_e32 v142, v189, v176
	v_mul_f32_e32 v226, v187, v181
	v_mov_b32_e32 v174, v181
	v_mov_b32_e32 v175, v180
	v_mul_f32_e32 v170, v187, v180
	s_waitcnt lgkmcnt(0)
	v_mfma_f32_32x32x16_bf16 v[50:65], v[130:133], v[138:141], v[50:65]
	ds_read_b128 v[130:133], v215 offset:59904
	v_fma_f32 v166, v186, v180, -v226
	v_fma_f32 v167, v187, v181, -v226
	v_fma_f32 v232, v186, v174, v170
	v_fma_f32 v233, v187, v175, v170
	v_mul_f32_e32 v172, v189, v177
	v_mov_b32_e32 v167, v232
	v_mov_b32_e32 v233, v166
	v_pk_fma_f32 v[162:163], v[188:189], v[176:177], v[172:173] op_sel_hi:[1,1,0] neg_lo:[0,0,1] neg_hi:[0,0,1]
	s_waitcnt lgkmcnt(0)
	v_mfma_f32_32x32x16_bf16 v[82:97], v[130:133], v[134:137], v[82:97]
	v_fma_f32 v136, v188, v168, v142
	v_fma_f32 v137, v189, v169, v142
	v_mul_f32_e64 v134, v194, v166
	v_mul_f32_e64 v135, v195, v167
	v_mov_b32_e32 v163, v136
	v_mov_b32_e32 v137, v162
	v_pk_mul_f32 v[164:165], v[200:201], v[162:163]
	v_cvt_pk_bf16_f32 v244, v180, v166
	v_pk_fma_f32 v[172:173], v[198:199], v[136:137], v[164:165]
	v_mfma_f32_32x32x16_bf16 v[18:33], v[130:133], v[138:141], v[18:33]
	ds_read_b128 v[130:133], v215 offset:55360
	ds_read_b128 v[138:141], v217 offset:36928
	ds_read_b128 v[142:145], v217 offset:41536
	v_fma_f32 v164, v198, v136, -v164
	v_fma_f32 v165, v199, v137, -v165
	v_cvt_pk_bf16_f32 v162, v176, v162


; #define MFMA32(a, b, c) __builtin_amdgcn_mfma_f32_32x32x16_bf16((a), (b), (c), 0, 0, 0)
; DI unsigned pk2(float a, float b) { f32v2 v = {a, b}; return __builtin_bit_cast(unsigned, __builtin_convertvector(v, bf16v2)); }
;   DI void gen(int kt, int q, float cd, float sd, uint4& rc, uint4& rs) const {
;     const int row = q >> 2, seg = q & 3;
;     const int ks = ks0 + row; const int sst = kt * 32 + seg * 8;
;     const int idx = (ks * sst) & (S - 1);
;     const float f = (float)idx * invS;
;     const float c0 = __builtin_amdgcn_cosf(f), s0 = __builtin_amdgcn_sinf(f);
;     const float c1 = c0 * cd - s0 * sd, s1 = s0 * cd + c0 * sd;
;     const float c2 = c1 * cd - s1 * sd, s2 = s1 * cd + c1 * sd;
;     const float c3 = c2 * cd - s2 * sd, s3 = s2 * cd + c2 * sd;
;     const float c4 = c3 * cd - s3 * sd, s4 = s3 * cd + c3 * sd;
;     const float c5 = c4 * cd - s4 * sd, s5 = s4 * cd + c4 * sd;
;     const float c6 = c5 * cd - s5 * sd, s6 = s5 * cd + c5 * sd;
;     const float c7 = c6 * cd - s6 * sd, s7 = s6 * cd + c6 * sd;
;     rc = make_uint4(pk2(c0, c1), pk2(c2, c3), pk2(c4, c5), pk2(c6, c7));
;     rs = make_uint4(pk2(-s0, -s1), pk2(-s2, -s3), pk2(-s4, -s5), pk2(-s6, -s7));
;   }
;   DI void load(int kt, int tid, uint4& r0, uint4& r1, uint4& r2, uint4& r3) const { gen(kt, tid, cd0, sd0, r0, r1); gen(kt, tid + 256, cd1, sd1, r2, r3); }
; DI void dft_mma(const bf16_t* sA, f32x16 (&accP)[2][2], f32x16 (&accQ)[2][2], int moff, int noff) {
;   const bf16_t* sB = sA + TILE_E;
; #pragma unroll
;   for (int kk = 0; kk < 4; kk++) {
;     bf16x8 fm0 = *(const bf16x8*)(sB + moff + kk * 16);
;     bf16x8 fm1 = *(const bf16x8*)(sB + moff + 32 * LDT + kk * 16);
;     bf16x8 fn0 = *(const bf16x8*)(sA + noff + kk * 16);
;     bf16x8 fn1 = *(const bf16x8*)(sA + noff + 32 * LDT + kk * 16);
;     if (kk < 2) {
;       accP[0][0] = MFMA32(fm0, fn0, accP[0][0]); accP[0][1] = MFMA32(fm0, fn1, accP[0][1]);
;       accP[1][0] = MFMA32(fm1, fn0, accP[1][0]); accP[1][1] = MFMA32(fm1, fn1, accP[1][1]);
;     } else {
;       accQ[0][0] = MFMA32(fm0, fn0, accQ[0][0]); accQ[0][1] = MFMA32(fm0, fn1, accQ[0][1]);
;       accQ[1][0] = MFMA32(fm1, fn0, accQ[1][0]); accQ[1][1] = MFMA32(fm1, fn1, accQ[1][1]);
;     }
;   }
	s_min_u32 s8, s10, s93
	s_waitcnt lgkmcnt(1)
	v_mfma_f32_32x32x16_bf16 v[98:113], v[130:133], v[138:141], v[98:113]
	s_mov_b32 s9, s91
	s_lshl_b64 s[8:9], s[8:9], 10
	s_add_i32 s10, s10, 2
	s_cmp_ge_u32 s11, s92
	s_waitcnt lgkmcnt(0)
	v_mfma_f32_32x32x16_bf16 v[34:49], v[130:133], v[142:145], v[34:49]
	ds_read_b128 v[130:133], v215 offset:59968
	s_waitcnt lgkmcnt(0)
	v_mfma_f32_32x32x16_bf16 v[66:81], v[130:133], v[138:141], v[66:81]
	v_fma_f32 v138, v192, v232, v134
	v_fma_f32 v139, v193, v233, v135
	v_fma_f32 v134, v192, v232, -v134
	v_fma_f32 v135, v193, v233, -v135
	v_mov_b32_e32 v140, v138
	v_pk_mov_b32 v[138:139], v[134:135], v[138:139] op_sel:[1,0]
	v_mov_b32_e32 v141, v135
	v_pk_mul_f32 v[138:139], v[194:195], v[138:139]
	v_mfma_f32_32x32x16_bf16 v[2:17], v[130:133], v[142:145], v[2:17]
	ds_read_b128 v[130:133], v215 offset:55328
	ds_read_b128 v[168:171], v217 offset:36896
	ds_read_b128 v[226:229], v217 offset:41504
	v_fma_f32 v174, v192, v140, v138
	v_fma_f32 v175, v193, v141, v139
	v_pk_fma_f32 v[138:139], v[192:193], v[140:141], v[138:139] neg_lo:[0,0,1] neg_hi:[0,0,1]
	v_pk_mov_b32 v[142:143], v[164:165], v[172:173] op_sel:[1,0]
	v_cvt_pk_bf16_f32 v245, v135, v139
	v_mov_b32_e32 v144, v172
	s_waitcnt lgkmcnt(1)
	v_mfma_f32_32x32x16_bf16 v[114:129], v[130:133], v[168:171], v[114:129]
	v_mov_b32_e32 v145, v165
	v_add_f32_e64 v140, -v140, neg(0)
	v_add_f32_e64 v141, -v141, neg(0)
	v_xor_b32_e32 v141, 0x80000000, v136
	s_waitcnt lgkmcnt(0)
	v_mfma_f32_32x32x16_bf16 v[50:65], v[130:133], v[226:229], v[50:65]
	ds_read_b128 v[130:133], v215 offset:59936
	s_waitcnt lgkmcnt(0)
	v_mfma_f32_32x32x16_bf16 v[82:97], v[130:133], v[168:171], v[82:97]
	v_mul_f32_e64 v168, v200, v142
	v_mul_f32_e64 v169, v201, v143
	v_mov_b32_e32 v142, v174
	v_mov_b32_e32 v143, v139
	v_fma_f32 v178, v198, v144, v168
	v_fma_f32 v179, v199, v145, v169
	v_mfma_f32_32x32x16_bf16 v[18:33], v[130:133], v[226:229], v[18:33]
	v_pk_mov_b32 v[130:131], v[138:139], v[174:175] op_sel:[1,0]
	v_xor_b32_e32 v174, 0x80000000, v174
	v_pk_mul_f32 v[130:131], v[194:195], v[130:131]
	v_cvt_pk_bf16_f32 v175, v140, v174
	v_pk_fma_f32 v[132:133], v[192:193], v[142:143], v[130:131]
	v_pk_fma_f32 v[130:131], v[192:193], v[142:143], v[130:131] neg_lo:[0,0,1] neg_hi:[0,0,1]
	v_mov_b32_e32 v142, v132
	v_pk_mov_b32 v[132:133], v[130:131], v[132:133] op_sel:[1,0]
	v_mov_b32_e32 v143, v131
	v_pk_mul_f32 v[132:133], v[194:195], v[132:133]

; DI unsigned pk2(float a, float b) { f32v2 v = {a, b}; return __builtin_bit_cast(unsigned, __builtin_convertvector(v, bf16v2)); }
;   DI void load(int kt, int tid, uint4& r0, uint4& r1, uint4& r2, uint4& r3) const { r0 = ld1(kt, 0, tid); r1 = ld1(kt, 1, tid); r2 = ld1(kt, 2, tid); r3 = ld1(kt, 3, tid); }
;   DI void load(int kt, int tid, uint4& r0, uint4& r1, uint4& r2, uint4& r3) const { r0 = ld1(kt, 0, tid); r1 = ld1(kt, 1, tid); r2 = ld1(kt, 2, tid); r3 = ld1(kt, 3, tid); }
;   DI void load(int kt, int tid, uint4& r0, uint4& r1, uint4& r2, uint4& r3) const { r0 = ld1(kt, 0, tid); r1 = ld1(kt, 1, tid); r2 = ld1(kt, 2, tid); r3 = ld1(kt, 3, tid); }
;   DI void load(int kt, int tid, uint4& r0, uint4& r1, uint4& r2, uint4& r3) const { r0 = ld1(kt, 0, tid); r1 = ld1(kt, 1, tid); r2 = ld1(kt, 2, tid); r3 = ld1(kt, 3, tid); }
;   DI void gen(int kt, int q, float cd, float sd, uint4& rc, uint4& rs) const {
;     const int row = q >> 2, seg = q & 3;
;     const int ks = ks0 + row; const int sst = kt * 32 + seg * 8;
;     const int idx = (ks * sst) & (S - 1);
;     const float f = (float)idx * invS;
;     const float c0 = __builtin_amdgcn_cosf(f), s0 = __builtin_amdgcn_sinf(f);
;     const float c1 = c0 * cd - s0 * sd, s1 = s0 * cd + c0 * sd;
;     const float c2 = c1 * cd - s1 * sd, s2 = s1 * cd + c1 * sd;
;     const float c3 = c2 * cd - s2 * sd, s3 = s2 * cd + c2 * sd;
;     const float c4 = c3 * cd - s3 * sd, s4 = s3 * cd + c3 * sd;
;     const float c5 = c4 * cd - s4 * sd, s5 = s4 * cd + c4 * sd;
;     const float c6 = c5 * cd - s5 * sd, s6 = s5 * cd + c5 * sd;
;     const float c7 = c6 * cd - s6 * sd, s7 = s6 * cd + c6 * sd;
;     rc = make_uint4(pk2(c0, c1), pk2(c2, c3), pk2(c4, c5), pk2(c6, c7));
;     rs = make_uint4(pk2(-s0, -s1), pk2(-s2, -s3), pk2(-s4, -s5), pk2(-s6, -s7));
;   }
;   DI void load(int kt, int tid, uint4& r0, uint4& r1, uint4& r2, uint4& r3) const { gen(kt, tid, cd0, sd0, r0, r1); gen(kt, tid + 256, cd1, sd1, r2, r3); }
	v_pk_fma_f32 v[228:229], v[192:193], v[142:143], v[132:133]
	v_pk_fma_f32 v[132:133], v[192:193], v[142:143], v[132:133] neg_lo:[0,0,1] neg_hi:[0,0,1]
	v_mov_b32_e32 v138, v228
	v_cvt_pk_bf16_f32 v246, v131, v133
	v_pk_mov_b32 v[130:131], v[132:133], v[228:229] op_sel:[1,0]
	v_mov_b32_e32 v139, v133
	v_pk_mul_f32 v[130:131], v[194:195], v[130:131]
	v_cvt_pk_bf16_f32 v174, -v181, -v232
	v_pk_fma_f32 v[134:135], v[192:193], v[138:139], v[130:131]
	v_pk_fma_f32 v[130:131], v[192:193], v[138:139], v[130:131] neg_lo:[0,0,1] neg_hi:[0,0,1]
	v_xor_b32_e32 v176, 0x80000000, v178
	v_mov_b32_e32 v135, v131
	v_mul_f32_e32 v130, v196, v134
	v_pk_fma_f32 v[132:133], v[196:197], v[134:135], v[130:131] op_sel_hi:[1,1,0] neg_lo:[0,0,1] neg_hi:[0,0,1]
	v_pk_add_f32 v[136:137], v[144:145], 0 neg_lo:[1,1] neg_hi:[1,1]
	v_cvt_pk_bf16_f32 v247, v131, v133
	v_pk_fma_f32 v[130:131], v[198:199], v[144:145], v[168:169] neg_lo:[0,0,1] neg_hi:[0,0,1]
	v_mov_b32_e32 v132, v178
	v_pk_mov_b32 v[138:139], v[130:131], v[178:179] op_sel:[1,0]
	v_mov_b32_e32 v133, v131
	v_pk_mul_f32 v[138:139], v[200:201], v[138:139]
	v_cvt_pk_bf16_f32 v163, v165, v131
	v_pk_fma_f32 v[168:169], v[198:199], v[132:133], v[138:139]
	v_pk_fma_f32 v[132:133], v[198:199], v[132:133], v[138:139] neg_lo:[0,0,1] neg_hi:[0,0,1]
	v_mov_b32_e32 v226, v168
	v_pk_mov_b32 v[130:131], v[132:133], v[168:169] op_sel:[1,0]
	v_mov_b32_e32 v227, v133
	v_pk_mul_f32 v[130:131], v[200:201], v[130:131]
	v_cvt_pk_bf16_f32 v178, -v177, v141
	v_pk_fma_f32 v[138:139], v[198:199], v[226:227], v[130:131] neg_lo:[0,0,1] neg_hi:[0,0,1]
	v_pk_fma_f32 v[230:231], v[198:199], v[226:227], v[130:131]
	v_cvt_pk_bf16_f32 v164, v133, v139
	v_pk_mov_b32 v[132:133], v[138:139], v[230:231] op_sel:[1,0]
	v_mov_b32_e32 v130, v230
	v_mov_b32_e32 v131, v139
	v_pk_mul_f32 v[132:133], v[200:201], v[132:133]

; #define MFMA32(a, b, c) __builtin_amdgcn_mfma_f32_32x32x16_bf16((a), (b), (c), 0, 0, 0)
; DI unsigned pk2(float a, float b) { f32v2 v = {a, b}; return __builtin_bit_cast(unsigned, __builtin_convertvector(v, bf16v2)); }
;   DI void gen(int kt, int q, float cd, float sd, uint4& rc, uint4& rs) const {
;     const int row = q >> 2, seg = q & 3;
;     const int ks = ks0 + row; const int sst = kt * 32 + seg * 8;
;     const int idx = (ks * sst) & (S - 1);
;     const float f = (float)idx * invS;
;     const float c0 = __builtin_amdgcn_cosf(f), s0 = __builtin_amdgcn_sinf(f);
;     const float c1 = c0 * cd - s0 * sd, s1 = s0 * cd + c0 * sd;
;     const float c2 = c1 * cd - s1 * sd, s2 = s1 * cd + c1 * sd;
;     const float c3 = c2 * cd - s2 * sd, s3 = s2 * cd + c2 * sd;
;     const float c4 = c3 * cd - s3 * sd, s4 = s3 * cd + c3 * sd;
;     const float c5 = c4 * cd - s4 * sd, s5 = s4 * cd + c4 * sd;
;     const float c6 = c5 * cd - s5 * sd, s6 = s5 * cd + c5 * sd;
;     const float c7 = c6 * cd - s6 * sd, s7 = s6 * cd + c6 * sd;
;     rc = make_uint4(pk2(c0, c1), pk2(c2, c3), pk2(c4, c5), pk2(c6, c7));
;     rs = make_uint4(pk2(-s0, -s1), pk2(-s2, -s3), pk2(-s4, -s5), pk2(-s6, -s7));
;   }
;   DI void load(int kt, int tid, uint4& r0, uint4& r1, uint4& r2, uint4& r3) const { gen(kt, tid, cd0, sd0, r0, r1); gen(kt, tid + 256, cd1, sd1, r2, r3); }
; DI void dft_mma(const bf16_t* sA, f32x16 (&accP)[2][2], f32x16 (&accQ)[2][2], int moff, int noff) {
;   const bf16_t* sB = sA + TILE_E;
; #pragma unroll
;   for (int kk = 0; kk < 4; kk++) {
;     bf16x8 fm0 = *(const bf16x8*)(sB + moff + kk * 16);
;     bf16x8 fm1 = *(const bf16x8*)(sB + moff + 32 * LDT + kk * 16);
;     bf16x8 fn0 = *(const bf16x8*)(sA + noff + kk * 16);
;     bf16x8 fn1 = *(const bf16x8*)(sA + noff + 32 * LDT + kk * 16);
;     if (kk < 2) {
;       accP[0][0] = MFMA32(fm0, fn0, accP[0][0]); accP[0][1] = MFMA32(fm0, fn1, accP[0][1]);
;       accP[1][0] = MFMA32(fm1, fn0, accP[1][0]); accP[1][1] = MFMA32(fm1, fn1, accP[1][1]);
;     } else {
;       accQ[0][0] = MFMA32(fm0, fn0, accQ[0][0]); accQ[0][1] = MFMA32(fm0, fn1, accQ[0][1]);
;       accQ[1][0] = MFMA32(fm1, fn0, accQ[1][0]); accQ[1][1] = MFMA32(fm1, fn1, accQ[1][1]);
;     }
;   }
	v_pk_fma_f32 v[138:139], v[198:199], v[130:131], v[132:133]
	v_pk_fma_f32 v[168:169], v[198:199], v[130:131], v[132:133] neg_lo:[0,0,1] neg_hi:[0,0,1]
	v_mul_f32_e32 v130, v210, v138
	v_mov_b32_e32 v139, v169
	v_pk_fma_f32 v[170:171], v[210:211], v[138:139], v[130:131] op_sel_hi:[1,1,0] neg_lo:[0,0,1] neg_hi:[0,0,1]
	ds_read_b128 v[240:243], v215 offset:55392
	ds_read_b128 v[130:133], v217 offset:36960
	v_cvt_pk_bf16_f32 v165, v169, v171
	ds_read_b128 v[166:169], v217 offset:41568
	ds_read_b128 v[170:173], v215 offset:60000
	v_pk_add_f32 v[140:141], v[142:143], 0 neg_lo:[1,1] neg_hi:[1,1]
	v_cvt_pk_bf16_f32 v179, v136, v176
	v_mov_b32_e32 v137, s9
	v_or_b32_e32 v136, s8, v0
	v_cvt_pk_bf16_f32 v176, v140, -v228

; DI unsigned pk2(float a, float b) { f32v2 v = {a, b}; return __builtin_bit_cast(unsigned, __builtin_convertvector(v, bf16v2)); }
;   DI void load(int kt, int tid, uint4& r0, uint4& r1, uint4& r2, uint4& r3) const { r0 = ld1(kt, 0, tid); r1 = ld1(kt, 1, tid); r2 = ld1(kt, 2, tid); r3 = ld1(kt, 3, tid); }
;   DI void load(int kt, int tid, uint4& r0, uint4& r1, uint4& r2, uint4& r3) const { r0 = ld1(kt, 0, tid); r1 = ld1(kt, 1, tid); r2 = ld1(kt, 2, tid); r3 = ld1(kt, 3, tid); }
;   DI void load(int kt, int tid, uint4& r0, uint4& r1, uint4& r2, uint4& r3) const { r0 = ld1(kt, 0, tid); r1 = ld1(kt, 1, tid); r2 = ld1(kt, 2, tid); r3 = ld1(kt, 3, tid); }
;   DI void load(int kt, int tid, uint4& r0, uint4& r1, uint4& r2, uint4& r3) const { r0 = ld1(kt, 0, tid); r1 = ld1(kt, 1, tid); r2 = ld1(kt, 2, tid); r3 = ld1(kt, 3, tid); }
;   DI void gen(int kt, int q, float cd, float sd, uint4& rc, uint4& rs) const {
;     const int row = q >> 2, seg = q & 3;
;     const int ks = ks0 + row; const int sst = kt * 32 + seg * 8;
;     const int idx = (ks * sst) & (S - 1);
;     const float f = (float)idx * invS;
;     const float c0 = __builtin_amdgcn_cosf(f), s0 = __builtin_amdgcn_sinf(f);
;     const float c1 = c0 * cd - s0 * sd, s1 = s0 * cd + c0 * sd;
;     const float c2 = c1 * cd - s1 * sd, s2 = s1 * cd + c1 * sd;
;     const float c3 = c2 * cd - s2 * sd, s3 = s2 * cd + c2 * sd;
;     const float c4 = c3 * cd - s3 * sd, s4 = s3 * cd + c3 * sd;
;     const float c5 = c4 * cd - s4 * sd, s5 = s4 * cd + c4 * sd;
;     const float c6 = c5 * cd - s5 * sd, s6 = s5 * cd + c5 * sd;
;     const float c7 = c6 * cd - s6 * sd, s7 = s6 * cd + c6 * sd;
;     rc = make_uint4(pk2(c0, c1), pk2(c2, c3), pk2(c4, c5), pk2(c6, c7));
;     rs = make_uint4(pk2(-s0, -s1), pk2(-s2, -s3), pk2(-s4, -s5), pk2(-s6, -s7));
;   }
;   DI void load(int kt, int tid, uint4& r0, uint4& r1, uint4& r2, uint4& r3) const { gen(kt, tid, cd0, sd0, r0, r1); gen(kt, tid + 256, cd1, sd1, r2, r3); }
; DI void dft_item(const Params& P, int g, int b, int ml, int ntc, bf16_t* smem) {
;     ...
;       { const int k3 = (kt + 3 < nk) ? kt + 3 : last; lb.load(k3, tid, b10, b11, b12, b13); }
	v_pk_add_f32 v[144:145], v[226:227], 0 neg_lo:[1,1] neg_hi:[1,1]
	v_lshl_add_u64 v[140:141], v[136:137], 0, v[202:203]
	v_lshl_add_u64 v[142:143], v[136:137], 0, v[204:205]
	v_cvt_pk_bf16_f32 v180, v144, -v230
	v_lshl_add_u64 v[144:145], v[136:137], 0, v[206:207]
	v_lshl_add_u64 v[136:137], v[136:137], 0, v[208:209]
	s_waitcnt lgkmcnt(2)
	v_mfma_f32_32x32x16_bf16 v[98:113], v[240:243], v[130:133], v[98:113]
	v_lshlrev_b64 v[136:137], 6, v[136:137]
	v_lshl_add_u64 v[230:231], v[224:225], 0, v[136:137]
	v_lshlrev_b64 v[140:141], 6, v[140:141]
	v_lshlrev_b64 v[142:143], 6, v[142:143]
	v_lshlrev_b64 v[144:145], 6, v[144:145]
	v_lshl_add_u64 v[140:141], v[224:225], 0, v[140:141]
	v_lshl_add_u64 v[226:227], v[224:225], 0, v[142:143]
	s_waitcnt lgkmcnt(0)
	v_mfma_f32_32x32x16_bf16 v[66:81], v[170:173], v[130:133], v[66:81]
	v_mul_f32_e64 v130, v186, v134
	v_mul_f32_e64 v131, v187, v135
	v_add_f32_e64 v134, -v134, neg(0)
	v_add_f32_e64 v135, -v135, neg(0)
	v_add_f32_e32 v136, v130, v131

; DI unsigned pk2(float a, float b) { f32v2 v = {a, b}; return __builtin_bit_cast(unsigned, __builtin_convertvector(v, bf16v2)); }
;   DI void load(int kt, int tid, uint4& r0, uint4& r1, uint4& r2, uint4& r3) const { r0 = ld1(kt, 0, tid); r1 = ld1(kt, 1, tid); r2 = ld1(kt, 2, tid); r3 = ld1(kt, 3, tid); }
;   DI void load(int kt, int tid, uint4& r0, uint4& r1, uint4& r2, uint4& r3) const { r0 = ld1(kt, 0, tid); r1 = ld1(kt, 1, tid); r2 = ld1(kt, 2, tid); r3 = ld1(kt, 3, tid); }
;   DI void load(int kt, int tid, uint4& r0, uint4& r1, uint4& r2, uint4& r3) const { r0 = ld1(kt, 0, tid); r1 = ld1(kt, 1, tid); r2 = ld1(kt, 2, tid); r3 = ld1(kt, 3, tid); }
;   DI void load(int kt, int tid, uint4& r0, uint4& r1, uint4& r2, uint4& r3) const { r0 = ld1(kt, 0, tid); r1 = ld1(kt, 1, tid); r2 = ld1(kt, 2, tid); r3 = ld1(kt, 3, tid); }
;   DI void gen(int kt, int q, float cd, float sd, uint4& rc, uint4& rs) const {
;     const int row = q >> 2, seg = q & 3;
;     const int ks = ks0 + row; const int sst = kt * 32 + seg * 8;
;     const int idx = (ks * sst) & (S - 1);
;     const float f = (float)idx * invS;
;     const float c0 = __builtin_amdgcn_cosf(f), s0 = __builtin_amdgcn_sinf(f);
;     const float c1 = c0 * cd - s0 * sd, s1 = s0 * cd + c0 * sd;
;     const float c2 = c1 * cd - s1 * sd, s2 = s1 * cd + c1 * sd;
;     const float c3 = c2 * cd - s2 * sd, s3 = s2 * cd + c2 * sd;
;     const float c4 = c3 * cd - s3 * sd, s4 = s3 * cd + c3 * sd;
;     const float c5 = c4 * cd - s4 * sd, s5 = s4 * cd + c4 * sd;
;     const float c6 = c5 * cd - s5 * sd, s6 = s5 * cd + c5 * sd;
;     const float c7 = c6 * cd - s6 * sd, s7 = s6 * cd + c6 * sd;
;     rc = make_uint4(pk2(c0, c1), pk2(c2, c3), pk2(c4, c5), pk2(c6, c7));
;     rs = make_uint4(pk2(-s0, -s1), pk2(-s2, -s3), pk2(-s4, -s5), pk2(-s6, -s7));
;   }
;   DI void load(int kt, int tid, uint4& r0, uint4& r1, uint4& r2, uint4& r3) const { gen(kt, tid, cd0, sd0, r0, r1); gen(kt, tid + 256, cd1, sd1, r2, r3); }
; DI void dft_item(const Params& P, int g, int b, int ml, int ntc, bf16_t* smem) {
;     ...
;       { const int k3 = (kt + 3 < nk) ? kt + 3 : last; lb.load(k3, tid, b10, b11, b12, b13); }
	v_cvt_pk_bf16_f32 v177, v134, -v136
	v_pk_mul_f32 v[134:135], v[188:189], v[138:139]
	v_lshl_add_u64 v[228:229], v[224:225], 0, v[144:145]
	global_load_dwordx4 v[142:145], v[140:141], off
	global_load_dwordx4 v[130:133], v[226:227], off
	v_add_f32_e32 v140, v134, v135
	v_pk_add_f32 v[138:139], v[138:139], 0 neg_lo:[1,1] neg_hi:[1,1]
	global_load_dwordx4 v[134:137], v[228:229], off

; DI float bflo(unsigned u) { return __uint_as_float(u << 16); }
; DI float bfhi(unsigned u) { return __uint_as_float(u & 0xffff0000u); }
; DI float bf2f_(bf16_t v) { return __uint_as_float((unsigned)v << 16); }
; DI float siluf_(float v) { return v / (1.f + __expf(-v)); }
; DI void store4(bf16_t* p, float a, float b, float c, float d) { *(uint2*)p = make_uint2(pk2(a, b), pk2(c, d)); }
;   DI void load(int kt, int tid, uint4& r0, uint4& r1, uint4& r2, uint4& r3) const { r0 = ld1(kt, 0, tid); r1 = ld1(kt, 1, tid); r2 = ld1(kt, 2, tid); r3 = ld1(kt, 3, tid); }
; DI size_t tix(size_t t, int f, int KT) { return ((t >> 7) * KT + (f >> 6)) * 8192 + (t & 127) * 64 + (f & 63); }
; DI void dft_item(const Params& P, int g, int b, int ml, int ntc, bf16_t* smem) {
;     ...
;       { const int k2 = (kt + 2 < nk) ? kt + 2 : last; la.load(k2, tid, a00, a01, a02, a03); }
;       GEMM_ST1(buf0, 0, a00, b00) GEMM_ST1(buf0, 1, a01, b01) GEMM_ST1(buf0, 2, a02, b02) GEMM_ST1(buf0, 3, a03, b03)
;       __syncthreads();
;     }
;   }
;   const float scale = rsqrtf((float)S * 128.f);
;   const size_t tb = (size_t)b * S;
; #pragma unroll
;   for (int j = 0; j < 2; j++) {
;     const int ks = ks0 + wn * 64 + j * 32 + l32;
;     const size_t t1 = tb + ks; const size_t t2 = tb + ((S - ks) & (S - 1));
; #pragma unroll
;     for (int i = 0; i < 2; i++)
; #pragma unroll
;       for (int rq = 0; rq < 4; rq++) {
;         const int ch = n0 + wm * 64 + i * 32 + 8 * rq + 4 * h;
;         const uint2 g1 = *(const uint2*)(Gd + t1 * 512 + ch);
;         const bf16_t* yh = Yt + (size_t)b * S * 1024 + ((size_t)(S >> 6) * 1024 + ch) * 32;
;         const float sgn = (ks & 1) ? -1.f : 1.f;
;         const float p0 = accP[i][j][4 * rq] + sgn * bf2f_(yh[0]), p1 = accP[i][j][4 * rq + 1] + sgn * bf2f_(yh[32]),
;                     p2 = accP[i][j][4 * rq + 2] + sgn * bf2f_(yh[64]), p3 = accP[i][j][4 * rq + 3] + sgn * bf2f_(yh[96]);
;         const float q0 = accQ[i][j][4 * rq], q1 = accQ[i][j][4 * rq + 1], q2 = accQ[i][j][4 * rq + 2], q3 = accQ[i][j][4 * rq + 3];
;         store4(cat + tix(t1, 512 + ch, 16), (p0 + q0) * scale * siluf_(bflo(g1.x)), (p1 + q1) * scale * siluf_(bfhi(g1.x)),
;                (p2 + q2) * scale * siluf_(bflo(g1.y)), (p3 + q3) * scale * siluf_(bfhi(g1.y)));
	v_cvt_pk_bf16_f32 v181, v138, -v140
	global_load_dwordx4 v[138:141], v[230:231], off
	v_mfma_f32_32x32x16_bf16 v[34:49], v[240:243], v[166:169], v[34:49]
	ds_write_b128 v212, v[244:247]
	s_waitcnt vmcnt(4)
	ds_write_b128 v214, v[158:161] offset:18432
	ds_write_b128 v212, v[174:177] offset:64
	ds_write_b128 v216, v[154:157] offset:18432
	ds_write_b128 v218, v[162:165]
	ds_write_b128 v220, v[150:153] offset:18432
	ds_write_b128 v218, v[178:181] offset:64
	ds_write_b128 v222, v[146:149] offset:18432
	s_waitcnt lgkmcnt(0)
	s_barrier
	v_mfma_f32_32x32x16_bf16 v[2:17], v[170:173], v[166:169], v[2:17]
	s_cbranch_scc0 .LBB0_54
	v_and_b32_e32 v0, 64, v184
	s_lshl_b64 s[10:11], s[2:3], s88
	v_readlane_b32 s2, v255, 46
	s_waitcnt vmcnt(0)
	v_or3_b32 v140, v0, s12, v191
	s_lshl_b64 s[12:13], s[10:11], 11
	v_add_u32_e32 v0, s2, v213
	v_readlane_b32 s2, v253, 2
	v_readlane_b32 s3, v253, 3
	s_add_u32 s14, s2, s12
	v_mov_b32_e32 v141, v1
	v_lshlrev_b32_e32 v131, 2, v185
	s_addc_u32 s15, s3, s13
	v_lshl_add_u64 v[132:133], s[10:11], 0, v[140:141]
	v_readlane_b32 s2, v253, 17
	v_or_b32_e32 v136, v0, v131
	v_add_u32_e32 v0, 0x200, v0
	v_lshlrev_b64 v[134:135], 10, v[132:133]
	v_readlane_b32 s3, v253, 18
	v_ashrrev_i32_e32 v138, 6, v0
	v_ashrrev_i32_e32 v139, 31, v138
	v_lshl_add_u64 v[146:147], s[2:3], 0, v[134:135]
	v_lshrrev_b64 v[134:135], 3, v[132:133]
	v_sub_u32_e32 v0, s89, v140
	v_and_b32_e32 v135, 0x1ff, v135
	v_and_b32_e32 v134, -16, v134
	v_and_b32_e32 v0, s29, v0
	v_lshl_add_u64 v[134:135], v[134:135], 0, v[138:139]
	v_lshl_add_u64 v[142:143], s[10:11], 0, v[0:1]
	v_lshlrev_b64 v[134:135], 14, v[134:135]
	v_lshlrev_b32_e32 v0, 7, v132
	v_lshl_add_u64 v[134:135], s[84:85], 0, v[134:135]
	v_and_b32_e32 v0, 0x3f80, v0
	v_lshlrev_b64 v[132:133], 10, v[142:143]
	v_lshl_add_u64 v[144:145], v[134:135], 0, v[0:1]
	v_lshl_add_u64 v[134:135], s[2:3], 0, v[132:133]
	v_lshrrev_b64 v[132:133], 3, v[142:143]
	v_and_b32_e32 v133, 0x1ff, v133
	v_and_b32_e32 v132, -16, v132
	v_lshl_add_u64 v[132:133], v[132:133], 0, v[138:139]
	v_lshlrev_b64 v[132:133], 14, v[132:133]
	v_lshlrev_b32_e32 v0, 7, v142
	v_lshl_add_u64 v[132:133], s[84:85], 0, v[132:133]
	v_and_b32_e32 v0, 0x3f80, v0
	v_ashrrev_i32_e32 v137, 31, v136
	v_lshl_add_u64 v[142:143], v[132:133], 0, v[0:1]
	v_lshl_add_u64 v[132:133], v[136:137], 0, s[6:7]
	v_lshlrev_b64 v[132:133], 6, v[132:133]
	v_lshl_add_u64 v[146:147], v[136:137], 1, v[146:147]
	v_lshl_add_u64 v[132:133], s[14:15], 0, v[132:133]
	global_load_dwordx2 v[148:149], v[146:147], off
	global_load_ushort v0, v[132:133], off
	global_load_ushort v141, v[132:133], off offset:64
	v_and_b32_e32 v130, 1, v184
	v_cmp_eq_u32_e32 vcc, 0, v130
	v_mov_b32_e32 v191, v1
	v_cmp_ne_u32_e64 s[8:9], 0, v140
	v_cndmask_b32_e64 v130, -1.0, 1.0, vcc
	s_waitcnt vmcnt(1)
	v_lshlrev_b32_e32 v150, 16, v0
	s_waitcnt vmcnt(0)
	v_lshlrev_b32_e32 v151, 16, v141
	v_pk_fma_f32 v[150:151], v[130:131], v[150:151], v[114:115] op_sel_hi:[0,1,1]
	global_load_ushort v0, v[132:133], off offset:128
	global_load_ushort v114, v[132:133], off offset:192
	v_and_b32_e32 v141, 0xffff0000, v148
	v_pk_add_f32 v[154:155], v[98:99], v[150:151]
	s_waitcnt vmcnt(0)
	v_lshlrev_b32_e32 v115, 16, v114
	v_lshlrev_b32_e32 v114, 16, v0
	v_lshlrev_b32_e32 v0, 16, v148
	v_mul_f32_e32 v148, 0xbfb8aa3b, v0
	v_exp_f32_e32 v152, v148
	v_mul_f32_e32 v148, 0xbfb8aa3b, v141
	v_exp_f32_e32 v153, v148
	v_pk_fma_f32 v[114:115], v[130:131], v[114:115], v[116:117] op_sel_hi:[0,1,1]
	v_pk_mul_f32 v[154:155], v[182:183], v[154:155]
	v_lshl_add_u64 v[116:117], v[144:145], 0, v[190:191]
	v_pk_add_f32 v[152:153], v[152:153], 1.0 op_sel_hi:[1,0]
	s_nop 0
	v_div_scale_f32 v148, s[2:3], v153, v153, v141
	v_rcp_f32_e32 v156, v148
	s_nop 0
	v_fma_f32 v157, -v148, v156, 1.0
	v_fmac_f32_e32 v156, v157, v156
	v_div_scale_f32 v157, vcc, v141, v153, v141
	v_mul_f32_e32 v158, v157, v156
	v_fma_f32 v159, -v148, v158, v157
	v_fmac_f32_e32 v158, v159, v156
	v_fma_f32 v148, -v148, v158, v157
	v_div_fmas_f32 v148, v148, v156, v158
	v_div_fixup_f32 v153, v148, v153, v141
	v_div_scale_f32 v141, s[2:3], v152, v152, v0
	v_rcp_f32_e32 v148, v141
	s_nop 0
	v_fma_f32 v156, -v141, v148, 1.0
	v_fmac_f32_e32 v148, v156, v148
	v_div_scale_f32 v156, vcc, v0, v152, v0
	v_mul_f32_e32 v157, v156, v148
	v_fma_f32 v158, -v141, v157, v156
	v_fmac_f32_e32 v157, v158, v148
	v_fma_f32 v141, -v141, v157, v156
	v_div_fmas_f32 v141, v141, v148, v157
	v_div_fixup_f32 v152, v141, v152, v0
	v_lshlrev_b32_e32 v0, 16, v149
	v_and_b32_e32 v141, 0xffff0000, v149
	v_mul_f32_e32 v148, 0xbfb8aa3b, v0
	v_mul_f32_e32 v149, 0xbfb8aa3b, v141
	v_exp_f32_e32 v148, v148
	v_exp_f32_e32 v149, v149
	v_pk_mul_f32 v[152:153], v[152:153], v[154:155]
	v_pk_add_f32 v[154:155], v[100:101], v[114:115]
	v_cvt_pk_bf16_f32 v152, v152, v153
	v_pk_add_f32 v[148:149], v[148:149], 1.0 op_sel_hi:[1,0]
	v_pk_mul_f32 v[154:155], v[182:183], v[154:155]
	v_div_scale_f32 v156, s[2:3], v149, v149, v141
	v_rcp_f32_e32 v157, v156
	s_nop 0
	v_fma_f32 v158, -v156, v157, 1.0
	v_fmac_f32_e32 v157, v158, v157
	v_div_scale_f32 v158, vcc, v141, v149, v141
	v_mul_f32_e32 v159, v158, v157
	v_fma_f32 v160, -v156, v159, v158
	v_fmac_f32_e32 v159, v160, v157
	v_fma_f32 v156, -v156, v159, v158
	v_div_fmas_f32 v156, v156, v157, v159
	v_div_fixup_f32 v149, v156, v149, v141
	v_div_scale_f32 v141, s[2:3], v148, v148, v0
	v_rcp_f32_e32 v156, v141
	s_nop 0
	v_fma_f32 v157, -v141, v156, 1.0
	v_fmac_f32_e32 v156, v157, v156
	v_div_scale_f32 v157, vcc, v0, v148, v0
	v_mul_f32_e32 v158, v157, v156
	v_fma_f32 v159, -v141, v158, v157
	v_fmac_f32_e32 v158, v159, v156
	v_fma_f32 v141, -v141, v158, v157
	v_div_fmas_f32 v141, v141, v156, v158
	v_div_fixup_f32 v148, v141, v148, v0
	v_pk_mul_f32 v[148:149], v[148:149], v[154:155]
	s_nop 0
	v_cvt_pk_bf16_f32 v153, v148, v149
	v_lshl_add_u64 v[148:149], v[136:137], 1, v[134:135]
	v_lshlrev_b32_e32 v134, 1, v131
	global_store_dwordx2 v[116:117], v[152:153], off
	s_and_saveexec_b64 s[2:3], s[8:9]
	s_cbranch_execz .LBB0_57
; DI float bflo(unsigned u) { return __uint_as_float(u << 16); }
; DI float bfhi(unsigned u) { return __uint_as_float(u & 0xffff0000u); }
; DI float siluf_(float v) { return v / (1.f + __expf(-v)); }
; DI void store4(bf16_t* p, float a, float b, float c, float d) { *(uint2*)p = make_uint2(pk2(a, b), pk2(c, d)); }
; DI size_t tix(size_t t, int f, int KT) { return ((t >> 7) * KT + (f >> 6)) * 8192 + (t & 127) * 64 + (f & 63); }
; DI void dft_item(const Params& P, int g, int b, int ml, int ntc, bf16_t* smem) {
;     ...
;         if (ks != 0) {
;           const uint2 g2 = *(const uint2*)(Gd + t2 * 512 + ch);
;           store4(cat + tix(t2, 512 + ch, 16), (p0 - q0) * scale * siluf_(bflo(g2.x)), (p1 - q1) * scale * siluf_(bfhi(g2.x)),
;                  (p2 - q2) * scale * siluf_(bflo(g2.y)), (p3 - q3) * scale * siluf_(bfhi(g2.y)));
	global_load_dwordx2 v[152:153], v[148:149], off
	v_mov_b32_e32 v135, v1
	v_lshl_add_u64 v[116:117], v[142:143], 0, v[134:135]
	v_pk_add_f32 v[98:99], v[150:151], v[98:99] neg_lo:[0,1] neg_hi:[0,1]
	v_pk_add_f32 v[100:101], v[114:115], v[100:101] neg_lo:[0,1] neg_hi:[0,1]
	v_pk_mul_f32 v[98:99], v[182:183], v[98:99]
	v_pk_mul_f32 v[100:101], v[182:183], v[100:101]
	s_waitcnt vmcnt(0)
	v_lshlrev_b32_e32 v0, 16, v152
	v_and_b32_e32 v131, 0xffff0000, v152
	v_mul_f32_e32 v135, 0xbfb8aa3b, v0
	v_exp_f32_e32 v150, v135
	v_mul_f32_e32 v135, 0xbfb8aa3b, v131
	v_exp_f32_e32 v151, v135
	s_nop 0
	v_pk_add_f32 v[150:151], v[150:151], 1.0 op_sel_hi:[1,0]
	s_nop 0
	v_div_scale_f32 v135, s[18:19], v151, v151, v131
	v_rcp_f32_e32 v141, v135
	s_nop 0
	v_fma_f32 v152, -v135, v141, 1.0
	v_fmac_f32_e32 v141, v152, v141
	v_div_scale_f32 v152, vcc, v131, v151, v131
	v_mul_f32_e32 v154, v152, v141
	v_fma_f32 v155, -v135, v154, v152
	v_fmac_f32_e32 v154, v155, v141
	v_fma_f32 v135, -v135, v154, v152
	v_div_fmas_f32 v135, v135, v141, v154
	v_div_fixup_f32 v151, v135, v151, v131
	v_div_scale_f32 v131, s[18:19], v150, v150, v0
	v_rcp_f32_e32 v135, v131
	s_nop 0
	v_fma_f32 v141, -v131, v135, 1.0
	v_fmac_f32_e32 v135, v141, v135
	v_div_scale_f32 v141, vcc, v0, v150, v0
	v_mul_f32_e32 v152, v141, v135
	v_fma_f32 v154, -v131, v152, v141
	v_fmac_f32_e32 v152, v154, v135
	v_fma_f32 v131, -v131, v152, v141
	v_div_fmas_f32 v131, v131, v135, v152
	v_div_fixup_f32 v150, v131, v150, v0
	v_lshlrev_b32_e32 v0, 16, v153
	v_and_b32_e32 v131, 0xffff0000, v153
	v_mul_f32_e32 v114, 0xbfb8aa3b, v0
	v_mul_f32_e32 v115, 0xbfb8aa3b, v131
	v_exp_f32_e32 v114, v114
	v_exp_f32_e32 v115, v115
	v_pk_mul_f32 v[98:99], v[98:99], v[150:151]
	v_pk_add_f32 v[114:115], v[114:115], 1.0 op_sel_hi:[1,0]
	s_nop 0
	v_div_scale_f32 v135, s[18:19], v115, v115, v131
	v_rcp_f32_e32 v141, v135
	v_cvt_pk_bf16_f32 v98, v98, v99
	v_fma_f32 v150, -v135, v141, 1.0
	v_fmac_f32_e32 v141, v150, v141
	v_div_scale_f32 v150, vcc, v131, v115, v131
	v_mul_f32_e32 v151, v150, v141
	v_fma_f32 v152, -v135, v151, v150
	v_fmac_f32_e32 v151, v152, v141
	v_fma_f32 v135, -v135, v151, v150
	v_div_fmas_f32 v135, v135, v141, v151
	v_div_fixup_f32 v115, v135, v115, v131
	v_div_scale_f32 v131, s[18:19], v114, v114, v0
	v_rcp_f32_e32 v135, v131
	s_nop 0
	v_fma_f32 v141, -v131, v135, 1.0
	v_fmac_f32_e32 v135, v141, v135
	v_div_scale_f32 v141, vcc, v0, v114, v0
	v_mul_f32_e32 v150, v141, v135
	v_fma_f32 v151, -v131, v150, v141
	v_fmac_f32_e32 v150, v151, v135
	v_fma_f32 v131, -v131, v150, v141
	v_div_fmas_f32 v131, v131, v135, v150
	v_div_fixup_f32 v114, v131, v114, v0
	v_pk_mul_f32 v[100:101], v[100:101], v[114:115]
	s_nop 0
	v_cvt_pk_bf16_f32 v99, v100, v101
	global_store_dwordx2 v[116:117], v[98:99], off
